# previous + mixer part A: the wave's 16 token rows are touched into L2 before the per-token loop
# baseline (speedup 1.0000x reference)
; __device__ __forceinline__ void phase_mixer(const Args& a, LAS unsigned char* lds, int l, int bid, int G, int dostore, int wave) {
;     ...
;             { u32x4 w = (u32x4){0u, 0u, 0u, 0u}; if (!seq_start(t0)) w = *(const u32x4*)(Z + (size_t)(t0 - 1) * ZW + 1024 + c0); unpack8(w, prev); }
;             { const u32x4 w = *(const u32x4*)(Z + (size_t)t0 * ZW + 1024 + c0); unpack8(w, cur); }
; #pragma unroll 4
;             for (int i = 0; i < 16; ++i) {
;                 const int t = t0 + i;
;                 { u32x4 w = (u32x4){0u, 0u, 0u, 0u}; if (!(t + 1 >= MTOT || seq_start(t + 1))) w = *(const u32x4*)(Z + (size_t)(t + 1) * ZW + 1024 + c0); unpack8(w, nxt); }
;                 float bg[8]; { const u32x4 w = *(const u32x4*)(Z + (size_t)t * ZW + c0); unpack8(w, bg); }
.LBB0_185:
	s_ashr_i32 s23, s22, 31
	s_lshl_b64 s[22:23], s[22:23], 12
	s_waitcnt vmcnt(18)
	v_lshl_add_u64 v[36:37], v[48:49], 0, s[22:23]
	global_load_dwordx4 v[84:87], v[36:37], off offset:2048
	s_waitcnt vmcnt(1)
	v_lshlrev_b32_e32 v91, 16, v32
	v_and_b32_e32 v90, 0xffff0000, v32
	v_lshlrev_b32_e32 v89, 16, v33
	v_and_b32_e32 v88, 0xffff0000, v33
	v_and_b32_e32 v41, 0xffff0000, v34
	v_lshlrev_b32_e32 v40, 16, v34
	v_and_b32_e32 v43, 0xffff0000, v35
	v_lshlrev_b32_e32 v42, 16, v35
	s_waitcnt vmcnt(0)
	v_lshlrev_b32_e32 v83, 16, v84
	v_and_b32_e32 v82, 0xffff0000, v84
	v_lshlrev_b32_e32 v47, 16, v85
	v_and_b32_e32 v46, 0xffff0000, v85
	v_and_b32_e32 v37, 0xffff0000, v86
	v_lshlrev_b32_e32 v36, 16, v86
	v_and_b32_e32 v39, 0xffff0000, v87
	v_lshlrev_b32_e32 v38, 16, v87
	s_mov_b32 s22, s10
	s_ashr_i32 s23, s10, 31
	s_lshl_b64 s[26:27], s[22:23], 12
	v_lshl_add_u64 v[248:249], v[48:49], 0, s[26:27]
	s_mov_b64 s[26:27], 0x1000
	global_load_dwordx4 v[244:247], v[248:249], off
	global_load_dwordx4 v[244:247], v[248:249], off offset:2048
	v_lshl_add_u64 v[248:249], v[248:249], 0, s[26:27]
	global_load_dwordx4 v[244:247], v[248:249], off
	global_load_dwordx4 v[244:247], v[248:249], off offset:2048
	v_lshl_add_u64 v[248:249], v[248:249], 0, s[26:27]
	global_load_dwordx4 v[244:247], v[248:249], off
	global_load_dwordx4 v[244:247], v[248:249], off offset:2048
	v_lshl_add_u64 v[248:249], v[248:249], 0, s[26:27]
	global_load_dwordx4 v[244:247], v[248:249], off
	global_load_dwordx4 v[244:247], v[248:249], off offset:2048
	v_lshl_add_u64 v[248:249], v[248:249], 0, s[26:27]
	global_load_dwordx4 v[244:247], v[248:249], off
	global_load_dwordx4 v[244:247], v[248:249], off offset:2048
	v_lshl_add_u64 v[248:249], v[248:249], 0, s[26:27]
	global_load_dwordx4 v[244:247], v[248:249], off
	global_load_dwordx4 v[244:247], v[248:249], off offset:2048
	v_lshl_add_u64 v[248:249], v[248:249], 0, s[26:27]
	global_load_dwordx4 v[244:247], v[248:249], off
	global_load_dwordx4 v[244:247], v[248:249], off offset:2048
	v_lshl_add_u64 v[248:249], v[248:249], 0, s[26:27]
	global_load_dwordx4 v[244:247], v[248:249], off
	global_load_dwordx4 v[244:247], v[248:249], off offset:2048
	v_lshl_add_u64 v[248:249], v[248:249], 0, s[26:27]
	global_load_dwordx4 v[244:247], v[248:249], off
	global_load_dwordx4 v[244:247], v[248:249], off offset:2048
	v_lshl_add_u64 v[248:249], v[248:249], 0, s[26:27]
	global_load_dwordx4 v[244:247], v[248:249], off
	global_load_dwordx4 v[244:247], v[248:249], off offset:2048
	v_lshl_add_u64 v[248:249], v[248:249], 0, s[26:27]
	global_load_dwordx4 v[244:247], v[248:249], off
	global_load_dwordx4 v[244:247], v[248:249], off offset:2048
	v_lshl_add_u64 v[248:249], v[248:249], 0, s[26:27]
	global_load_dwordx4 v[244:247], v[248:249], off
	global_load_dwordx4 v[244:247], v[248:249], off offset:2048
	v_lshl_add_u64 v[248:249], v[248:249], 0, s[26:27]
	global_load_dwordx4 v[244:247], v[248:249], off
	global_load_dwordx4 v[244:247], v[248:249], off offset:2048
	v_lshl_add_u64 v[248:249], v[248:249], 0, s[26:27]
	global_load_dwordx4 v[244:247], v[248:249], off
	global_load_dwordx4 v[244:247], v[248:249], off offset:2048
	v_lshl_add_u64 v[248:249], v[248:249], 0, s[26:27]
	global_load_dwordx4 v[244:247], v[248:249], off
	global_load_dwordx4 v[244:247], v[248:249], off offset:2048
	v_lshl_add_u64 v[248:249], v[248:249], 0, s[26:27]
	global_load_dwordx4 v[244:247], v[248:249], off
	global_load_dwordx4 v[244:247], v[248:249], off offset:2048
	v_lshl_add_u64 v[248:249], v[248:249], 0, s[26:27]
	s_add_i32 s22, s10, 16
	s_cmp_gt_i32 s22, 0xffff
	s_cbranch_scc1 .Lmix_touch_done
	global_load_dwordx4 v[244:247], v[248:249], off offset:2048
.Lmix_touch_done:
	s_branch .LBB0_187
.LBB0_186:
	s_add_i32 s2, s2, 4
	s_cmp_eq_u32 s2, 16
	s_cbranch_scc1 .LBB0_205
